# attention MODE0 steady loop: LDS-DMA issue point split by wave half (waves 0-3 at the phase boundary, waves 4-7 after PV mfma 5) to halve DMA queue contention
# baseline (speedup 1.0000x reference)
.LBB0_796:
	v_lshlrev_b32_e32 v53, 1, v52
	v_lshlrev_b32_e32 v52, 4, v52
	v_and_b32_e32 v214, 32, v53
	v_and_b32_e32 v52, 0xc0, v52
	v_lshl_or_b32 v213, v209, 8, v52
	v_add_u32_e32 v52, 0, v214
	v_add3_u32 v219, v52, v211, v213
	v_max3_f32 v52, v36, v37, v20
	v_max3_f32 v53, v38, v39, v21
	s_and_b32 s0, s22, 0x3fffffc0
	v_max3_f32 v52, v52, v22, v23
	v_max3_f32 v53, v53, v42, v43
	s_lshl_b32 s0, s0, 2
	v_max3_f32 v52, v52, v40, v41
	v_max3_f32 v53, v53, v26, v27
	s_add_i32 s1, s64, 0x100
	v_max3_f32 v52, v52, v24, v25
	v_max3_f32 v53, v53, v46, v47
	s_add_i32 s53, s0, 0
	v_max3_f32 v52, v52, v44, v45
	v_max3_f32 v53, v53, v30, v31
	s_lshr_b32 s48, s1, 6
	v_max3_f32 v52, v52, v28, v29
	v_max3_f32 v53, v53, v50, v51
	s_mov_b64 s[22:23], 0x60000
	v_max3_f32 v52, v52, v48, v49
	v_max3_f32 v53, v53, v34, v35
	s_cmp_lg_u32 0, -1
	v_max3_f32 v52, v52, v32, v33
	s_mov_b64 s[10:11], 0x20000
	v_max_f32_e32 v52, v52, v53
	v_lshl_add_u64 v[190:191], v[84:85], 0, s[10:11]
	v_mov_b32_e32 v53, v52
	s_nop 1
	v_permlane32_swap_b32_e32 v52, v53
	v_max_f32_e32 v52, v52, v53
	s_mov_b32 s0, 1
	v_max_f32_e32 v52, v52, v228
	s_mov_b32 s24, 0
	v_add_f32_e32 v217, v3, v52
	v_sub_f32_e32 v53, v36, v52
	v_sub_f32_e32 v54, v37, v52
	v_sub_f32_e32 v55, v38, v52
	v_sub_f32_e32 v56, v39, v52
	v_sub_f32_e32 v57, v40, v52
	s_nop 0
	v_xor_b32_e32 v36, 0x80000000, v217
	v_sub_f32_e32 v58, v41, v52
	v_sub_f32_e32 v59, v42, v52
	v_sub_f32_e32 v60, v43, v52
	v_sub_f32_e32 v61, v44, v52
	v_sub_f32_e32 v62, v45, v52
	v_sub_f32_e32 v63, v46, v52
	v_sub_f32_e32 v64, v47, v52
	v_sub_f32_e32 v65, v48, v52
	v_sub_f32_e32 v66, v49, v52
	v_sub_f32_e32 v67, v50, v52
	v_sub_f32_e32 v83, v51, v52
	v_mov_b32_e32 v37, v36
	v_mov_b32_e32 v38, v36
	v_mov_b32_e32 v39, v36
	v_mov_b32_e32 v40, v36
	v_mov_b32_e32 v41, v36
	v_mov_b32_e32 v42, v36
	v_mov_b32_e32 v43, v36
	v_mov_b32_e32 v44, v36
	v_mov_b32_e32 v45, v36
	v_mov_b32_e32 v46, v36
	v_mov_b32_e32 v47, v36
	v_mov_b32_e32 v48, v36
	v_mov_b32_e32 v49, v36
	v_mov_b32_e32 v50, v36
	v_mov_b32_e32 v51, v36
	v_sub_f32_e32 v20, v20, v52
	v_sub_f32_e32 v21, v21, v52
	s_waitcnt vmcnt(0) lgkmcnt(0)
	s_barrier
	v_sub_f32_e32 v22, v22, v52
	v_sub_f32_e32 v23, v23, v52
	v_sub_f32_e32 v24, v24, v52
	v_sub_f32_e32 v25, v25, v52
	v_sub_f32_e32 v26, v26, v52
	v_sub_f32_e32 v27, v27, v52
	v_sub_f32_e32 v28, v28, v52
	v_sub_f32_e32 v29, v29, v52
	v_sub_f32_e32 v30, v30, v52
	v_sub_f32_e32 v31, v31, v52
	v_sub_f32_e32 v32, v32, v52
	v_sub_f32_e32 v33, v33, v52
	v_sub_f32_e32 v34, v34, v52
	v_sub_f32_e32 v35, v35, v52
	v_exp_f32_e32 v68, v53
	v_exp_f32_e32 v52, v20
	v_exp_f32_e32 v53, v21
	v_lshl_add_u64 v[20:21], v[188:189], 0, s[22:23]
	s_mov_b32 m0, s46
	s_nop 0
	global_load_lds_dwordx4 v[20:21], off
	s_cselect_b32 s1, 0, 0
	s_add_i32 s1, s1, s45
	s_add_i32 s1, s1, 0x8000
	s_mov_b32 m0, s1
	s_nop 0
	global_load_lds_dwordx4 v[190:191], off
	ds_read_b128 v[180:183], v218 offset:8192
	ds_read_b128 v[176:179], v218 offset:8704
	ds_read_b128 v[172:175], v218 offset:10240
	ds_read_b128 v[168:171], v218 offset:10752
	ds_read_b128 v[164:167], v218 offset:12288
	ds_read_b128 v[160:163], v218 offset:12800
	ds_read_b128 v[156:159], v218 offset:14336
	ds_read_b128 v[152:155], v218 offset:14848
	v_exp_f32_e32 v69, v54
	v_exp_f32_e32 v70, v55
	v_exp_f32_e32 v71, v56
	v_exp_f32_e32 v72, v57
	v_exp_f32_e32 v73, v58
	v_exp_f32_e32 v74, v59
	v_exp_f32_e32 v75, v60
	v_exp_f32_e32 v76, v61
	v_exp_f32_e32 v77, v62
	v_exp_f32_e32 v78, v63
	v_exp_f32_e32 v79, v64
	v_exp_f32_e32 v80, v65
	v_exp_f32_e32 v81, v66
	v_exp_f32_e32 v82, v67
	v_exp_f32_e32 v83, v83
	v_exp_f32_e32 v54, v22
	v_exp_f32_e32 v55, v23
	v_exp_f32_e32 v56, v24
	v_exp_f32_e32 v57, v25
	v_exp_f32_e32 v58, v26
	v_exp_f32_e32 v59, v27
	v_exp_f32_e32 v60, v28
	v_exp_f32_e32 v61, v29
	v_exp_f32_e32 v62, v30
	v_exp_f32_e32 v63, v31
	v_exp_f32_e32 v64, v32
	v_exp_f32_e32 v65, v33
	v_exp_f32_e32 v66, v34
	v_exp_f32_e32 v67, v35
	s_waitcnt vmcnt(2) lgkmcnt(0)
	s_barrier
	s_andn2_b64 vcc, exec, s[4:5]
	v_cmp_gt_u32_e64 s[4:5], 32, v1
	s_cbranch_vccnz .LBB0_812
	v_lshlrev_b32_e32 v20, 4, v209
	s_mov_b64 s[10:11], 0xa0000
	v_add_u32_e32 v203, s53, v20
	v_mov_b64_e32 v[34:35], v[18:19]
	s_add_i32 s1, s48, -5
	v_lshl_add_u32 v202, v208, 2, s53
	v_lshl_add_u64 v[192:193], v[84:85], 0, s[22:23]
	v_lshl_add_u64 v[194:195], v[188:189], 0, s[10:11]
	s_movk_i32 s24, 0x4000
	s_movk_i32 s25, 0x2000
	s_mov_b32 s10, 0
	v_mov_b32_e32 v220, 0
	v_mov_b64_e32 v[32:33], v[16:17]
	v_mov_b64_e32 v[30:31], v[14:15]
	v_mov_b64_e32 v[28:29], v[12:13]
	v_mov_b64_e32 v[26:27], v[10:11]
	v_mov_b64_e32 v[24:25], v[8:9]
	v_mov_b64_e32 v[22:23], v[6:7]
	v_mov_b64_e32 v[20:21], v[4:5]
	s_mov_b64 s[98:99], exec
	v_and_b32_e32 v224, 0xffff0000, v36
	v_sub_f32_e32 v225, v224, v36
	v_exp_f32_e32 v225, v225
	v_bfe_i32 v196, v132, 0, 1
	v_mov_b32_e32 v250, 0
	v_mov_b32_e32 v251, 0
	v_mov_b32_e32 v252, 0
	v_mov_b32_e32 v253, 0
	v_mov_b32_e32 v247, 0
	v_mov_b32_e32 v248, 0
	v_mov_b32_e32 v249, 0
	v_mov_b32_e32 v222, 0
	v_mov_b32_e32 v223, 0
	s_mov_b32 exec_hi, 0
	v_mov_b32_e32 v250, 0x3f80
	v_mov_b32_e32 v223, 0xf180
	v_lshrrev_b32_e32 v222, 16, v224
	s_mov_b64 exec, s[98:99]
	v_readfirstlane_b32 s98, v192
	v_readfirstlane_b32 s99, v193
	s_sub_u32 s98, s98, 0x1000000
	s_subb_u32 s99, s99, 0
	v_subrev_u32_e32 v199, s98, v192
	v_subrev_u32_e32 v198, s98, v194
	v_add_u32_e32 v203, 0xfffe0000, v199
	v_add_u32_e32 v202, 0xfffe0000, v198
	v_and_b32_e32 v224, v225, v196
	v_mul_f32_e32 v4, v225, v4
	v_mul_f32_e32 v5, v225, v5
	v_mul_f32_e32 v6, v225, v6
	v_mul_f32_e32 v7, v225, v7
	v_mul_f32_e32 v8, v225, v8
	v_mul_f32_e32 v9, v225, v9
	v_mul_f32_e32 v10, v225, v10
	v_mul_f32_e32 v11, v225, v11
	v_mul_f32_e32 v12, v225, v12
	v_mul_f32_e32 v13, v225, v13
	v_mul_f32_e32 v14, v225, v14
	v_mul_f32_e32 v15, v225, v15
	v_mul_f32_e32 v16, v225, v16
	v_mul_f32_e32 v17, v225, v17
	v_mul_f32_e32 v18, v225, v18
	v_mul_f32_e32 v19, v225, v19
	v_mul_f32_e32 v20, v225, v20
	v_mul_f32_e32 v21, v225, v21
	v_mul_f32_e32 v22, v225, v22
	v_mul_f32_e32 v23, v225, v23
	v_mul_f32_e32 v24, v225, v24
	v_mul_f32_e32 v25, v225, v25
	v_mul_f32_e32 v26, v225, v26
	v_mul_f32_e32 v27, v225, v27
	v_mul_f32_e32 v28, v225, v28
	v_mul_f32_e32 v29, v225, v29
	v_mul_f32_e32 v30, v225, v30
	v_mul_f32_e32 v31, v225, v31
	v_mul_f32_e32 v32, v225, v32
	v_mul_f32_e32 v33, v225, v33
	v_mul_f32_e32 v34, v225, v34
	v_mul_f32_e32 v35, v225, v35
	v_mul_f32_e32 v52, v224, v52
	v_mul_f32_e32 v53, v224, v53
	v_mul_f32_e32 v54, v224, v54
	v_mul_f32_e32 v55, v224, v55
	v_mul_f32_e32 v56, v224, v56
	v_mul_f32_e32 v57, v224, v57
	v_mul_f32_e32 v58, v224, v58
	v_mul_f32_e32 v59, v224, v59
	v_mul_f32_e32 v60, v224, v60
	v_mul_f32_e32 v61, v224, v61
	v_mul_f32_e32 v62, v224, v62
	v_mul_f32_e32 v63, v224, v63
	v_mul_f32_e32 v64, v224, v64
	v_mul_f32_e32 v65, v224, v65
	v_mul_f32_e32 v66, v224, v66
	v_mul_f32_e32 v67, v224, v67
	v_mul_f32_e32 v68, v224, v68
	v_mul_f32_e32 v69, v224, v69
	v_mul_f32_e32 v70, v224, v70
	v_mul_f32_e32 v71, v224, v71
	v_mul_f32_e32 v72, v224, v72
	v_mul_f32_e32 v73, v224, v73
	v_mul_f32_e32 v74, v224, v74
	v_mul_f32_e32 v75, v224, v75
	v_mul_f32_e32 v76, v224, v76
	v_mul_f32_e32 v77, v224, v77
	v_mul_f32_e32 v78, v224, v78
	v_mul_f32_e32 v79, v224, v79
	v_mul_f32_e32 v80, v224, v80
	v_mul_f32_e32 v81, v224, v81
	v_mul_f32_e32 v82, v224, v82
	v_mul_f32_e32 v83, v224, v83
	v_mul_f32_e32 v220, v225, v220
	v_bfe_i32 v196, v132, 1, 1
	v_bfi_b32 v246, v196, v222, v223
	s_mov_b32 s101, 2
	v_readfirstlane_b32 s100, v0
	s_lshr_b32 s100, s100, 8
	s_nop 1
	v_mfma_f32_32x32x16_bf16 v[36:51], v[250:253], v[246:249], 0
	s_branch .LBB0_798

.LBB0_798:
	v_add_u32_e32 v197, s10, v219
	ds_read_b64_tr_b16 v[184:185], v197 offset:24576
	ds_read_b64_tr_b16 v[186:187], v197 offset:25088
	v_mfma_f32_32x32x16_bf16 v[100:115], v[180:183], v[116:119], v[36:51]
	v_add_f32_e32 v84, v68, v69
	v_add_f32_e32 v84, v70, v84
	v_add_f32_e32 v84, v71, v84
	v_cvt_pk_bf16_f32 v148, v68, v69
	v_add_f32_e32 v84, v72, v84
	v_cvt_pk_bf16_f32 v149, v70, v71
	v_add_f32_e32 v84, v73, v84
	ds_read_b64_tr_b16 v[180:181], v197 offset:28672
	ds_read_b64_tr_b16 v[182:183], v197 offset:29184
	v_add_f32_e32 v68, v74, v84
	v_mfma_f32_32x32x16_bf16 v[84:99], v[176:179], v[116:119], v[36:51]
	v_add_f32_e32 v68, v75, v68
	v_add_f32_e32 v68, v76, v68
	v_add_f32_e32 v136, v77, v68
	v_cvt_pk_bf16_f32 v150, v72, v73
	v_cvt_pk_bf16_f32 v151, v74, v75
	ds_read_b64_tr_b16 v[68:69], v197 offset:25600
	ds_read_b64_tr_b16 v[70:71], v197 offset:26112
	v_mfma_f32_32x32x16_bf16 v[100:115], v[172:175], v[120:123], v[100:115]
	v_add_f32_e32 v72, v78, v136
	v_add_f32_e32 v72, v79, v72
	v_add_f32_e32 v72, v80, v72
	v_add_f32_e32 v136, v81, v72
	v_cvt_pk_bf16_f32 v144, v76, v77
	v_cvt_pk_bf16_f32 v145, v78, v79
	ds_read_b64_tr_b16 v[72:73], v197 offset:29696
	ds_read_b64_tr_b16 v[74:75], v197 offset:30208
	v_mfma_f32_32x32x16_bf16 v[84:99], v[168:171], v[120:123], v[84:99]
	v_add_f32_e32 v76, v82, v136
	v_add_f32_e32 v76, v83, v76
	v_add_f32_e32 v76, v52, v76
	v_add_f32_e32 v136, v53, v76
	v_cvt_pk_bf16_f32 v146, v80, v81
	v_cvt_pk_bf16_f32 v147, v82, v83
	ds_read_b64_tr_b16 v[76:77], v197 offset:26624
	ds_read_b64_tr_b16 v[78:79], v197 offset:27136
	v_mfma_f32_32x32x16_bf16 v[100:115], v[164:167], v[124:127], v[100:115]
	v_add_f32_e32 v80, v54, v136
	v_add_f32_e32 v80, v55, v80
	v_cvt_pk_bf16_f32 v140, v52, v53
	v_add_f32_e32 v80, v56, v80
	v_cvt_pk_bf16_f32 v141, v54, v55
	v_add_f32_e32 v80, v57, v80
	ds_read_b64_tr_b16 v[52:53], v197 offset:30720
	ds_read_b64_tr_b16 v[54:55], v197 offset:31232
	v_mfma_f32_32x32x16_bf16 v[84:99], v[160:163], v[124:127], v[84:99]
	v_add_f32_e32 v80, v58, v80
	v_add_f32_e32 v80, v59, v80
	v_cvt_pk_bf16_f32 v142, v56, v57
	v_add_f32_e32 v80, v60, v80
	v_cvt_pk_bf16_f32 v143, v58, v59
	v_add_f32_e32 v80, v61, v80
	ds_read_b64_tr_b16 v[56:57], v197 offset:27648
	ds_read_b64_tr_b16 v[58:59], v197 offset:28160
	v_mfma_f32_32x32x16_bf16 v[100:115], v[156:159], v[128:131], v[100:115]
	v_add_f32_e32 v80, v62, v80
	v_add_f32_e32 v80, v63, v80
	v_cvt_pk_bf16_f32 v136, v60, v61
	v_add_f32_e32 v80, v64, v80
	v_cvt_pk_bf16_f32 v137, v62, v63
	v_add_f32_e32 v80, v65, v80
	ds_read_b64_tr_b16 v[60:61], v197 offset:31744
	ds_read_b64_tr_b16 v[62:63], v197 offset:32256
	v_mfma_f32_32x32x16_bf16 v[84:99], v[152:155], v[128:131], v[84:99]
	v_add_f32_e32 v80, v66, v80
	v_cvt_pk_bf16_f32 v138, v64, v65
	v_add_f32_e32 v80, v67, v80
	v_cvt_pk_bf16_f32 v139, v66, v67
	s_cmp_eq_u32 s100, 0
	s_cbranch_scc0 .Ldma_e1
	s_add_i32 s10, s25, s46
	s_mov_b32 m0, s10
	s_nop 0
	global_load_lds_dwordx4 v202, s[98:99]
	s_add_i32 s10, s24, s47
	s_mov_b32 m0, s10
	s_nop 0
	global_load_lds_dwordx4 v203, s[98:99]
.Ldma_e1:
	v_add_f32_e32 v204, v220, v80
.LBB0_799:
	s_waitcnt lgkmcnt(14)
	v_mfma_f32_32x32x16_bf16 v[20:35], v[148:151], v[184:187], v[20:35]
	v_exp_f32_e32 v100, v100
	v_exp_f32_e32 v101, v101
	v_exp_f32_e32 v102, v102
	v_exp_f32_e32 v103, v103
	s_waitcnt lgkmcnt(12)
	v_mfma_f32_32x32x16_bf16 v[4:19], v[148:151], v[180:183], v[4:19]
	v_exp_f32_e32 v104, v104
	v_exp_f32_e32 v105, v105
	v_exp_f32_e32 v106, v106
	v_exp_f32_e32 v107, v107
	v_add_u32_e32 v80, s24, v218
	ds_read_b128 v[64:67], v80
	ds_read_b128 v[180:183], v80 offset:512
	s_waitcnt lgkmcnt(12)
	v_mfma_f32_32x32x16_bf16 v[20:35], v[144:147], v[68:71], v[20:35]
	v_exp_f32_e32 v108, v108
	v_exp_f32_e32 v109, v109
	v_exp_f32_e32 v110, v110
	v_exp_f32_e32 v111, v111
	ds_read_b128 v[184:187], v80 offset:2048
	ds_read_b128 v[176:179], v80 offset:2560
	s_waitcnt lgkmcnt(12)
	v_mfma_f32_32x32x16_bf16 v[4:19], v[144:147], v[72:75], v[4:19]
	v_exp_f32_e32 v112, v112
	v_exp_f32_e32 v113, v113
	v_exp_f32_e32 v114, v114
	v_exp_f32_e32 v115, v115
	ds_read_b128 v[172:175], v80 offset:4096
	ds_read_b128 v[168:171], v80 offset:4608
	s_waitcnt lgkmcnt(12)
	v_mfma_f32_32x32x16_bf16 v[20:35], v[140:143], v[76:79], v[20:35]
	v_exp_f32_e32 v84, v84
	v_exp_f32_e32 v85, v85
	v_exp_f32_e32 v86, v86
	v_exp_f32_e32 v87, v87
	s_cmp_eq_u32 s100, 0
	s_cbranch_scc1 .Ldma_l1
	s_add_i32 s10, s25, s46
	s_mov_b32 m0, s10
	s_nop 0
	global_load_lds_dwordx4 v202, s[98:99]
	s_add_i32 s10, s24, s47
	s_mov_b32 m0, s10
	s_nop 0
	global_load_lds_dwordx4 v203, s[98:99]
.Ldma_l1:
	ds_read_b128 v[164:167], v80 offset:6144
	ds_read_b128 v[160:163], v80 offset:6656
	s_waitcnt lgkmcnt(12)
	v_mfma_f32_32x32x16_bf16 v[4:19], v[140:143], v[52:55], v[4:19]
	v_exp_f32_e32 v88, v88
	v_exp_f32_e32 v89, v89
	v_exp_f32_e32 v90, v90
	v_exp_f32_e32 v91, v91
	s_waitcnt lgkmcnt(10)
	v_mfma_f32_32x32x16_bf16 v[20:35], v[136:139], v[56:59], v[20:35]
	v_exp_f32_e32 v92, v92
	v_exp_f32_e32 v93, v93
	v_exp_f32_e32 v94, v94
	v_exp_f32_e32 v95, v95
	s_cmp_eq_u32 s101, 32
	s_cbranch_scc1 .Lattn0_rot

.LBB0_801:
	v_add_u32_e32 v197, s25, v219
	ds_read_b64_tr_b16 v[152:153], v197 offset:24576
	ds_read_b64_tr_b16 v[154:155], v197 offset:25088
	v_mfma_f32_32x32x16_bf16 v[68:83], v[64:67], v[116:119], v[36:51]
	v_add_f32_e32 v52, v100, v101
	v_add_f32_e32 v52, v102, v52
	v_add_f32_e32 v52, v103, v52
	v_cvt_pk_bf16_f32 v148, v100, v101
	v_add_f32_e32 v52, v104, v52
	v_cvt_pk_bf16_f32 v149, v102, v103
	v_add_f32_e32 v52, v105, v52
	ds_read_b64_tr_b16 v[156:157], v197 offset:28672
	ds_read_b64_tr_b16 v[158:159], v197 offset:29184
	v_add_f32_e32 v52, v106, v52
	v_add_f32_e32 v52, v107, v52
	v_add_f32_e32 v52, v108, v52
	v_add_f32_e32 v136, v109, v52
	v_mfma_f32_32x32x16_bf16 v[52:67], v[180:183], v[116:119], v[36:51]
	v_cvt_pk_bf16_f32 v150, v104, v105
	v_cvt_pk_bf16_f32 v151, v106, v107
	ds_read_b64_tr_b16 v[100:101], v197 offset:25600
	ds_read_b64_tr_b16 v[102:103], v197 offset:26112
	v_mfma_f32_32x32x16_bf16 v[68:83], v[184:187], v[120:123], v[68:83]
	v_add_f32_e32 v104, v110, v136
	v_add_f32_e32 v104, v111, v104
	v_add_f32_e32 v104, v112, v104
	v_add_f32_e32 v136, v113, v104
	v_cvt_pk_bf16_f32 v144, v108, v109
	v_cvt_pk_bf16_f32 v145, v110, v111
	ds_read_b64_tr_b16 v[104:105], v197 offset:29696
	ds_read_b64_tr_b16 v[106:107], v197 offset:30208
	v_mfma_f32_32x32x16_bf16 v[52:67], v[176:179], v[120:123], v[52:67]
	v_add_f32_e32 v108, v114, v136
	v_add_f32_e32 v108, v115, v108
	v_add_f32_e32 v108, v84, v108
	v_add_f32_e32 v136, v85, v108
	v_cvt_pk_bf16_f32 v146, v112, v113
	v_cvt_pk_bf16_f32 v147, v114, v115
	ds_read_b64_tr_b16 v[108:109], v197 offset:26624
	ds_read_b64_tr_b16 v[110:111], v197 offset:27136
	v_mfma_f32_32x32x16_bf16 v[68:83], v[172:175], v[124:127], v[68:83]
	v_add_f32_e32 v112, v86, v136
	v_add_f32_e32 v112, v87, v112
	v_cvt_pk_bf16_f32 v140, v84, v85
	v_add_f32_e32 v112, v88, v112
	v_cvt_pk_bf16_f32 v141, v86, v87
	v_add_f32_e32 v112, v89, v112
	ds_read_b64_tr_b16 v[84:85], v197 offset:30720
	ds_read_b64_tr_b16 v[86:87], v197 offset:31232
	v_mfma_f32_32x32x16_bf16 v[52:67], v[168:171], v[124:127], v[52:67]
	v_add_f32_e32 v112, v90, v112
	v_add_f32_e32 v112, v91, v112
	v_cvt_pk_bf16_f32 v142, v88, v89
	v_add_f32_e32 v112, v92, v112
	v_cvt_pk_bf16_f32 v143, v90, v91
	v_add_f32_e32 v112, v93, v112
	ds_read_b64_tr_b16 v[88:89], v197 offset:27648
	ds_read_b64_tr_b16 v[90:91], v197 offset:28160
	v_mfma_f32_32x32x16_bf16 v[68:83], v[164:167], v[128:131], v[68:83]
	v_add_f32_e32 v112, v94, v112
	v_add_f32_e32 v112, v95, v112
	v_cvt_pk_bf16_f32 v136, v92, v93
	v_add_f32_e32 v112, v96, v112
	v_cvt_pk_bf16_f32 v137, v94, v95
	v_add_f32_e32 v112, v97, v112
	ds_read_b64_tr_b16 v[92:93], v197 offset:31744
	ds_read_b64_tr_b16 v[94:95], v197 offset:32256
	v_mfma_f32_32x32x16_bf16 v[52:67], v[160:163], v[128:131], v[52:67]
	v_add_f32_e32 v112, v98, v112
	v_cvt_pk_bf16_f32 v138, v96, v97
	v_add_f32_e32 v112, v99, v112
	v_cvt_pk_bf16_f32 v139, v98, v99
	v_add_f32_e32 v220, v204, v112
	s_cmp_eq_u32 s100, 0
	s_cbranch_scc0 .Ldma_e0
	s_add_i32 s10, s24, s46
	s_mov_b32 m0, s10
	s_nop 0
	global_load_lds_dwordx4 v198, s[98:99]
	s_add_i32 s10, s54, s47
	s_mov_b32 m0, s10
	s_nop 0
	global_load_lds_dwordx4 v199, s[98:99]
.Ldma_e0:
.LBB0_802:
	s_waitcnt lgkmcnt(14)
	v_mfma_f32_32x32x16_bf16 v[20:35], v[148:151], v[152:155], v[20:35]
	v_exp_f32_e32 v68, v68
	v_exp_f32_e32 v69, v69
	v_exp_f32_e32 v70, v70
	v_exp_f32_e32 v71, v71
	s_waitcnt lgkmcnt(12)
	v_mfma_f32_32x32x16_bf16 v[4:19], v[148:151], v[156:159], v[4:19]
	v_exp_f32_e32 v72, v72
	v_exp_f32_e32 v73, v73
	v_exp_f32_e32 v74, v74
	v_exp_f32_e32 v75, v75
	v_add_u32_e32 v96, s54, v218
	ds_read_b128 v[180:183], v96
	ds_read_b128 v[176:179], v96 offset:512
	s_waitcnt lgkmcnt(12)
	v_mfma_f32_32x32x16_bf16 v[20:35], v[144:147], v[100:103], v[20:35]
	v_exp_f32_e32 v76, v76
	v_exp_f32_e32 v77, v77
	v_exp_f32_e32 v78, v78
	v_exp_f32_e32 v79, v79
	ds_read_b128 v[172:175], v96 offset:2048
	ds_read_b128 v[168:171], v96 offset:2560
	s_waitcnt lgkmcnt(12)
	v_mfma_f32_32x32x16_bf16 v[4:19], v[144:147], v[104:107], v[4:19]
	v_exp_f32_e32 v80, v80
	v_exp_f32_e32 v81, v81
	v_exp_f32_e32 v82, v82
	v_exp_f32_e32 v83, v83
	ds_read_b128 v[164:167], v96 offset:4096
	ds_read_b128 v[160:163], v96 offset:4608
	s_waitcnt lgkmcnt(12)
	v_mfma_f32_32x32x16_bf16 v[20:35], v[140:143], v[108:111], v[20:35]
	v_exp_f32_e32 v52, v52
	v_exp_f32_e32 v53, v53
	v_exp_f32_e32 v54, v54
	v_exp_f32_e32 v55, v55
	s_cmp_eq_u32 s100, 0
	s_cbranch_scc1 .Ldma_l0
	s_add_i32 s10, s24, s46
	s_mov_b32 m0, s10
	s_nop 0
	global_load_lds_dwordx4 v198, s[98:99]
	s_add_i32 s10, s54, s47
	s_mov_b32 m0, s10
	s_nop 0
	global_load_lds_dwordx4 v199, s[98:99]
.Ldma_l0:
	ds_read_b128 v[156:159], v96 offset:6144
	ds_read_b128 v[152:155], v96 offset:6656
	s_waitcnt lgkmcnt(12)
	v_mfma_f32_32x32x16_bf16 v[4:19], v[140:143], v[84:87], v[4:19]
	v_exp_f32_e32 v56, v56
	v_exp_f32_e32 v57, v57
	v_exp_f32_e32 v58, v58
	v_exp_f32_e32 v59, v59
	s_waitcnt lgkmcnt(10)
	v_mfma_f32_32x32x16_bf16 v[20:35], v[136:139], v[88:91], v[20:35]
	v_exp_f32_e32 v60, v60
	v_exp_f32_e32 v61, v61
	v_exp_f32_e32 v62, v62
	v_exp_f32_e32 v63, v63
	v_bfe_i32 v196, v132, s101, 1
	v_bfi_b32 v246, v196, v222, v223
	s_waitcnt lgkmcnt(8)
	v_mfma_f32_32x32x16_bf16 v[4:19], v[136:139], v[92:95], v[4:19]
	v_exp_f32_e32 v64, v64
	v_exp_f32_e32 v65, v65
	v_exp_f32_e32 v66, v66
	v_exp_f32_e32 v67, v67
	v_mfma_f32_32x32x16_bf16 v[36:51], v[250:253], v[246:249], 0
	s_add_i32 s101, s101, 1
	s_add_i32 s0, s0, 2
	s_add_i32 s10, s54, 0x2000
	s_cmpk_lg_i32 s54, 0x4000
	s_cselect_b32 s42, s10, 0
	s_add_u32 s98, s98, s80
	s_addc_u32 s99, s99, s81
	s_cmp_ge_i32 s0, s1
	s_cbranch_scc1 .Lattn0_exit
	s_mov_b32 s10, s24
	s_mov_b32 s25, s54
	s_mov_b32 s24, s42
	s_branch .Lattn0_head
